# v10 + diff attention second-map epilogue: 16 scratch reloads issued up front (no per-row drain), attention epilogue flat ops made global
# speedup vs baseline: 1.0018x; 1.0018x over previous
; template <int D0> __device__ __forceinline__ void pv_one(f32x16& od, int vb, bf16x8 pa0, bf16x8 pa1, bf16x8 pa2, bf16x8 pa3) {
;     const s16x4 l0 = tr_read<v_rd_off(D0, 0, 0)>(vb), h0 = tr_read<v_rd_off(D0, 0, 1)>(vb), l1 = tr_read<v_rd_off(D0, 1, 0)>(vb), h1 = tr_read<v_rd_off(D0, 1, 1)>(vb);
;     const s16x4 l2 = tr_read<v_rd_off(D0, 2, 0)>(vb), h2 = tr_read<v_rd_off(D0, 2, 1)>(vb), l3 = tr_read<v_rd_off(D0, 3, 0)>(vb), h3 = tr_read<v_rd_off(D0, 3, 1)>(vb);
;     asm volatile("s_waitcnt lgkmcnt(0)" ::: "memory"); SBAR();
;     ...
;     od = __builtin_amdgcn_mfma_f32_32x32x16_bf16(pa0, PK(l0, h0), od, 0, 0, 0);
;     od = __builtin_amdgcn_mfma_f32_32x32x16_bf16(pa1, PK(l1, h1), od, 0, 0, 0);
;     od = __builtin_amdgcn_mfma_f32_32x32x16_bf16(pa2, PK(l2, h2), od, 0, 0, 0);
;     od = __builtin_amdgcn_mfma_f32_32x32x16_bf16(pa3, PK(l3, h3), od, 0, 0, 0);
;     ...
; }
; __device__ __forceinline__ void pv_d0(f32x16* o, int vb, bf16x8 pa0, bf16x8 pa1, bf16x8 pa2, bf16x8 pa3) {
;     pv_one<0>(o[0], vb, pa0, pa1, pa2, pa3); pv_one<1>(o[1], vb, pa0, pa1, pa2, pa3); pv_one<2>(o[2], vb, pa0, pa1, pa2, pa3); pv_one<3>(o[3], vb, pa0, pa1, pa2, pa3);
; }
; __device__ __forceinline__ void partialSM(f32x16& p0, f32x16& p1, float& m_reg, float& mn, float& alpha, const float C, const float thr) {
;     float pmax = p0[0];
; #pragma unroll
;     for (int r = 1; r < 16; ++r) pmax = fmaxf(pmax, p0[r]);
; #pragma unroll
;     for (int r = 0; r < 16; ++r) pmax = fmaxf(pmax, p1[r]);
;     { auto rr = __builtin_amdgcn_permlane32_swap(__float_as_uint(pmax), __float_as_uint(pmax), false, false);
;       pmax = fmaxf(__uint_as_float(rr[0]), __uint_as_float(rr[1])); }
;     if (__builtin_expect(__all(pmax - m_reg <= thr), 1)) { mn = m_reg; alpha = 1.f; }
;     else { mn = fmaxf(m_reg, pmax); alpha = __builtin_amdgcn_exp2f((m_reg - mn) * C); m_reg = mn; }
;     const float mnC = -mn * C;
; #pragma unroll
;     for (int r = 0; r < 16; ++r) p0[r] = fmaf(p0[r], C, mnC);
; #pragma unroll
;     for (int r = 0; r < 16; ++r) p1[r] = fmaf(p1[r], C, mnC);
; #pragma unroll
;     for (int r = 0; r < 16; ++r) p0[r] = __builtin_amdgcn_exp2f(p0[r]);
; }
; __device__ __forceinline__ void finishSM(f32x16& p0, f32x16& p1, float alpha, float& l_reg, bf16x8& pa0, bf16x8& pa1, bf16x8& pa2, bf16x8& pa3) {
; #pragma unroll
;     for (int r = 0; r < 16; ++r) p1[r] = __builtin_amdgcn_exp2f(p1[r]);
;     float ps = 0;
.LBB0_187:
	v_cndmask_b32_e64 v101, v101, v142, s[14:15]
	v_mul_f32_e32 v101, 0xbe38aa3b, v101
	v_fmamk_f32 v80, v80, 0x3e38aa3b, v101
	v_fmamk_f32 v81, v81, 0x3e38aa3b, v101
	v_fmamk_f32 v102, v82, 0x3e38aa3b, v101
	v_exp_f32_e32 v82, v80
	v_fmamk_f32 v103, v84, 0x3e38aa3b, v101
	v_exp_f32_e32 v84, v81
	v_fmamk_f32 v83, v83, 0x3e38aa3b, v101
	v_exp_f32_e32 v80, v102
	v_fmamk_f32 v64, v64, 0x3e38aa3b, v101
	v_exp_f32_e32 v83, v83
	v_fmamk_f32 v104, v85, 0x3e38aa3b, v101
	v_fmamk_f32 v113, v94, 0x3e38aa3b, v101
	v_fmamk_f32 v94, v75, 0x3e38aa3b, v101
	v_exp_f32_e32 v75, v103
	v_exp_f32_e32 v102, v64
	v_add_f32_e32 v64, 0, v82
	v_fmamk_f32 v105, v86, 0x3e38aa3b, v101
	v_exp_f32_e32 v81, v104
	v_add_f32_e32 v64, v84, v64
	v_fmamk_f32 v106, v87, 0x3e38aa3b, v101
	v_fmamk_f32 v112, v93, 0x3e38aa3b, v101
	v_fmamk_f32 v93, v74, 0x3e38aa3b, v101
	v_exp_f32_e32 v74, v105
	v_add_f32_e32 v64, v80, v64
	v_fmamk_f32 v107, v88, 0x3e38aa3b, v101
	v_fmamk_f32 v114, v95, 0x3e38aa3b, v101
	v_fmamk_f32 v95, v76, 0x3e38aa3b, v101
	v_exp_f32_e32 v76, v106
	v_add_f32_e32 v64, v83, v64
	v_fmamk_f32 v108, v89, 0x3e38aa3b, v101
	v_fmamk_f32 v109, v90, 0x3e38aa3b, v101
	v_fmamk_f32 v90, v71, 0x3e38aa3b, v101
	v_exp_f32_e32 v71, v107
	v_add_f32_e32 v64, v75, v64
	v_fmamk_f32 v111, v92, 0x3e38aa3b, v101
	v_fmamk_f32 v92, v73, 0x3e38aa3b, v101
	v_exp_f32_e32 v73, v108
	v_add_f32_e32 v64, v81, v64
	v_fmamk_f32 v110, v91, 0x3e38aa3b, v101
	v_fmamk_f32 v88, v69, 0x3e38aa3b, v101
	v_exp_f32_e32 v69, v109
	v_add_f32_e32 v64, v74, v64
	v_fmamk_f32 v91, v72, 0x3e38aa3b, v101
	v_exp_f32_e32 v72, v110
	v_add_f32_e32 v64, v76, v64
	v_fmamk_f32 v86, v67, 0x3e38aa3b, v101
	v_exp_f32_e32 v67, v111
	v_add_f32_e32 v64, v71, v64
	v_fmamk_f32 v89, v70, 0x3e38aa3b, v101
	v_exp_f32_e32 v70, v112
	v_add_f32_e32 v64, v73, v64
	v_fmamk_f32 v85, v66, 0x3e38aa3b, v101
	v_exp_f32_e32 v66, v113
	v_add_f32_e32 v64, v69, v64
	v_fmamk_f32 v87, v68, 0x3e38aa3b, v101
	v_exp_f32_e32 v68, v114
	v_add_f32_e32 v64, v72, v64
	v_fmamk_f32 v65, v65, 0x3e38aa3b, v101
	v_add_f32_e32 v64, v67, v64
	v_exp_f32_e32 v103, v65
	v_add_f32_e32 v64, v70, v64
	v_exp_f32_e32 v85, v85
	v_add_f32_e32 v64, v66, v64
	v_exp_f32_e32 v86, v86
	v_add_f32_e32 v64, v68, v64
	v_exp_f32_e32 v87, v87
	v_add_f32_e32 v64, v102, v64
	v_exp_f32_e32 v88, v88
	v_add_f32_e32 v64, v103, v64
	v_exp_f32_e32 v89, v89
	v_add_f32_e32 v64, v85, v64
	v_exp_f32_e32 v90, v90
	v_add_f32_e32 v64, v86, v64
	v_exp_f32_e32 v91, v91
	v_add_f32_e32 v64, v87, v64
	v_exp_f32_e32 v92, v92
	v_add_f32_e32 v64, v88, v64
	v_exp_f32_e32 v93, v93
	v_add_f32_e32 v64, v89, v64
	v_exp_f32_e32 v94, v94
	v_add_f32_e32 v64, v90, v64
	v_fmamk_f32 v77, v77, 0x3e38aa3b, v101
	v_exp_f32_e32 v95, v95
	v_add_f32_e32 v64, v91, v64
	v_fmamk_f32 v78, v78, 0x3e38aa3b, v101
	v_exp_f32_e32 v104, v77
	v_add_f32_e32 v64, v92, v64
	v_fmac_f32_e32 v101, 0x3e38aa3b, v79
	v_exp_f32_e32 v105, v78
	v_add_f32_e32 v64, v93, v64
	v_exp_f32_e32 v101, v101
	v_add_f32_e32 v64, v94, v64
	v_add_f32_e32 v64, v95, v64
	v_add_f32_e32 v64, v104, v64
	v_add_f32_e32 v64, v105, v64
	v_add_f32_e32 v64, v101, v64
	v_mov_b32_e32 v65, v64
	s_nop 1
	v_permlane32_swap_b32_e32 v64, v65
	v_cvt_pk_bf16_f32 v78, v82, v84
	v_cvt_pk_bf16_f32 v79, v80, v83
	v_cvt_pk_bf16_f32 v80, v75, v81
	v_cvt_pk_bf16_f32 v81, v74, v76
	v_cvt_pk_bf16_f32 v74, v71, v73
	v_cvt_pk_bf16_f32 v75, v69, v72
	v_cvt_pk_bf16_f32 v76, v67, v70
	v_cvt_pk_bf16_f32 v77, v66, v68
	v_cvt_pk_bf16_f32 v66, v102, v103
	v_cvt_pk_bf16_f32 v67, v85, v86
	v_cvt_pk_bf16_f32 v68, v87, v88
	v_cvt_pk_bf16_f32 v69, v89, v90
	v_cvt_pk_bf16_f32 v70, v91, v92
	v_cvt_pk_bf16_f32 v71, v93, v94
	v_cvt_pk_bf16_f32 v72, v95, v104
	v_cvt_pk_bf16_f32 v73, v105, v101
	s_nop 0
	v_permlane32_swap_b32_e32 v78, v80
	v_permlane32_swap_b32_e32 v79, v81
	v_permlane32_swap_b32_e32 v74, v76
	v_permlane32_swap_b32_e32 v75, v77
	v_permlane32_swap_b32_e32 v66, v68
	v_permlane32_swap_b32_e32 v67, v69
	v_permlane32_swap_b32_e32 v70, v72
	v_permlane32_swap_b32_e32 v71, v73
	ds_read_b64_tr_b16 v[82:83], v179 offset:0
	ds_read_b64_tr_b16 v[84:85], v179 offset:0x800
	ds_read_b64_tr_b16 v[86:87], v179 offset:0x1000
	ds_read_b64_tr_b16 v[88:89], v179 offset:0x1800
	ds_read_b64_tr_b16 v[90:91], v179 offset:0x2000
	ds_read_b64_tr_b16 v[92:93], v179 offset:0x2800
	ds_read_b64_tr_b16 v[102:103], v179 offset:0x3000
	ds_read_b64_tr_b16 v[104:105], v179 offset:0x3800
	s_waitcnt lgkmcnt(0)
	s_nop 0
	v_mfma_f32_32x32x16_bf16 v[48:63], v[78:81], v[82:85], v[48:63]
	ds_read_b64_tr_b16 v[82:83], v179 offset:0x200
	ds_read_b64_tr_b16 v[84:85], v179 offset:0xa00
	v_mfma_f32_32x32x16_bf16 v[48:63], v[74:77], v[86:89], v[48:63]
	ds_read_b64_tr_b16 v[86:87], v179 offset:0x1200
	ds_read_b64_tr_b16 v[88:89], v179 offset:0x1a00
	v_mfma_f32_32x32x16_bf16 v[48:63], v[66:69], v[90:93], v[48:63]
	ds_read_b64_tr_b16 v[90:91], v179 offset:0x2200
	ds_read_b64_tr_b16 v[92:93], v179 offset:0x2a00
	v_mfma_f32_32x32x16_bf16 v[48:63], v[70:73], v[102:105], v[48:63]
	ds_read_b64_tr_b16 v[102:103], v179 offset:0x3200
	ds_read_b64_tr_b16 v[104:105], v179 offset:0x3a00
	s_waitcnt lgkmcnt(0)
	v_mfma_f32_32x32x16_bf16 v[32:47], v[78:81], v[82:85], v[32:47]
	ds_read_b64_tr_b16 v[82:83], v179 offset:0x400
	ds_read_b64_tr_b16 v[84:85], v179 offset:0xc00
	v_mfma_f32_32x32x16_bf16 v[32:47], v[74:77], v[86:89], v[32:47]
	ds_read_b64_tr_b16 v[86:87], v179 offset:0x1400
	ds_read_b64_tr_b16 v[88:89], v179 offset:0x1c00
	v_mfma_f32_32x32x16_bf16 v[32:47], v[66:69], v[90:93], v[32:47]
	ds_read_b64_tr_b16 v[90:91], v179 offset:0x2400
	ds_read_b64_tr_b16 v[92:93], v179 offset:0x2c00
	v_mfma_f32_32x32x16_bf16 v[32:47], v[70:73], v[102:105], v[32:47]
	ds_read_b64_tr_b16 v[102:103], v179 offset:0x3400
	ds_read_b64_tr_b16 v[104:105], v179 offset:0x3c00
	s_waitcnt lgkmcnt(0)
; #define SBAR() __builtin_amdgcn_sched_barrier(0)
; __device__ __forceinline__ int crow(int r, int hi) { return (r & 3) + 8 * (r >> 2) + 4 * hi; }
; template <int OFF> __device__ __forceinline__ s16x4 tr_read(int vb) { s16x4 r; asm volatile("ds_read_b64_tr_b16 %0, %1 offset:%2" : "=&v"(r) : "v"(vb), "i"(OFF) : "memory"); return r; }
; template <int D0> __device__ __forceinline__ void pv_one(f32x16& od, int vb, bf16x8 pa0, bf16x8 pa1, bf16x8 pa2, bf16x8 pa3) {
;     const s16x4 l0 = tr_read<v_rd_off(D0, 0, 0)>(vb), h0 = tr_read<v_rd_off(D0, 0, 1)>(vb), l1 = tr_read<v_rd_off(D0, 1, 0)>(vb), h1 = tr_read<v_rd_off(D0, 1, 1)>(vb);
;     const s16x4 l2 = tr_read<v_rd_off(D0, 2, 0)>(vb), h2 = tr_read<v_rd_off(D0, 2, 1)>(vb), l3 = tr_read<v_rd_off(D0, 3, 0)>(vb), h3 = tr_read<v_rd_off(D0, 3, 1)>(vb);
;     asm volatile("s_waitcnt lgkmcnt(0)" ::: "memory"); SBAR();
;     ...
;     od = __builtin_amdgcn_mfma_f32_32x32x16_bf16(pa0, PK(l0, h0), od, 0, 0, 0);
;     od = __builtin_amdgcn_mfma_f32_32x32x16_bf16(pa1, PK(l1, h1), od, 0, 0, 0);
;     od = __builtin_amdgcn_mfma_f32_32x32x16_bf16(pa2, PK(l2, h2), od, 0, 0, 0);
;     od = __builtin_amdgcn_mfma_f32_32x32x16_bf16(pa3, PK(l3, h3), od, 0, 0, 0);
; template <int DQK, int DK1, int LDQ, int LDK, int LDKR, int LDV, int NQL, int SDEPTH>
; __device__ __forceinline__ void attn_core(const AttnArgs& a, char* lds, f32x16 (&o)[4]) {
;     ...
;     if (hi == 0) li_l[r32] = l_reg; asm volatile("s_waitcnt lgkmcnt(0)" ::: "memory");
; #pragma unroll
;     for (int r = 0; r < 16; ++r) { const float rl = __builtin_amdgcn_rcpf(li_l[crow(r, hi)]);
; #pragma unroll
;         for (int d = 0; d < 4; ++d) o[d][r] *= rl; }
;     __syncthreads();
	v_mfma_f32_32x32x16_bf16 v[16:31], v[78:81], v[82:85], v[16:31]
	ds_read_b64_tr_b16 v[82:83], v179 offset:0x600
	ds_read_b64_tr_b16 v[84:85], v179 offset:0xe00
	v_mfma_f32_32x32x16_bf16 v[16:31], v[74:77], v[86:89], v[16:31]
	ds_read_b64_tr_b16 v[86:87], v179 offset:0x1600
	ds_read_b64_tr_b16 v[88:89], v179 offset:0x1e00
	v_mfma_f32_32x32x16_bf16 v[16:31], v[66:69], v[90:93], v[16:31]
	ds_read_b64_tr_b16 v[90:91], v179 offset:0x2600
	ds_read_b64_tr_b16 v[92:93], v179 offset:0x2e00
	v_mfma_f32_32x32x16_bf16 v[16:31], v[70:73], v[102:105], v[16:31]
	ds_read_b64_tr_b16 v[102:103], v179 offset:0x3600
	ds_read_b64_tr_b16 v[104:105], v179 offset:0x3e00
	s_waitcnt lgkmcnt(0)
	v_mfma_f32_32x32x16_bf16 v[0:15], v[78:81], v[82:85], v[0:15]
	v_mfma_f32_32x32x16_bf16 v[0:15], v[74:77], v[86:89], v[0:15]
	v_mfma_f32_32x32x16_bf16 v[0:15], v[66:69], v[90:93], v[0:15]
	v_mfma_f32_32x32x16_bf16 v[0:15], v[70:73], v[102:105], v[0:15]
	s_and_saveexec_b64 s[14:15], s[12:13]
	v_add_f32_e32 v66, v98, v99
	v_fmac_f32_e32 v66, v178, v143
	v_add_f32_e32 v64, v64, v65
	v_fmac_f32_e32 v64, v66, v100
	ds_write_b32 v177, v64 offset:49152
	s_or_b64 exec, exec, s[14:15]
	s_waitcnt lgkmcnt(0)
	v_add_u32_e32 v82, v161, v96
	ds_read_b128 v[74:77], v82 offset:49152
	ds_read_b128 v[78:81], v82 offset:49184
	v_mov_b32_e32 v68, v16
	s_nop 0
	v_mov_b32_e32 v69, v0
	v_mov_b32_e32 v0, v17
	s_waitcnt lgkmcnt(1)
	v_rcp_f32_e32 v16, v75
	v_rcp_f32_e32 v66, v74
	v_mov_b32_e32 v64, v48
	v_mov_b32_e32 v65, v32
	v_pk_mul_f32 v[70:71], v[0:1], v[16:17] op_sel_hi:[1,0]
	v_rcp_f32_e32 v0, v76
	v_mov_b32_e32 v32, v49
	v_pk_mul_f32 v[64:65], v[64:65], v[66:67] op_sel_hi:[1,0]
	v_pk_mul_f32 v[66:67], v[68:69], v[66:67] op_sel_hi:[1,0]
	v_pk_mul_f32 v[68:69], v[32:33], v[16:17] op_sel_hi:[1,0]
	v_mov_b32_e32 v16, v50
	v_mov_b32_e32 v17, v34
	v_pk_mul_f32 v[72:73], v[16:17], v[0:1] op_sel_hi:[1,0]
	v_mov_b32_e32 v16, v18
	v_mov_b32_e32 v17, v2
	v_pk_mul_f32 v[74:75], v[16:17], v[0:1] op_sel_hi:[1,0]
	v_rcp_f32_e32 v16, v77
	v_mov_b32_e32 v32, v20
	s_waitcnt lgkmcnt(0)
	v_rcp_f32_e32 v20, v79
	v_mov_b32_e32 v34, v51
	v_rcp_f32_e32 v18, v78
	v_mov_b32_e32 v33, v4
	v_mov_b32_e32 v4, v21
	v_pk_mul_f32 v[0:1], v[34:35], v[16:17] op_sel_hi:[1,0]
	v_pk_mul_f32 v[34:35], v[4:5], v[20:21] op_sel_hi:[1,0]
	v_rcp_f32_e32 v4, v80
	ds_read_b128 v[76:79], v82 offset:49216
	v_mov_b32_e32 v2, v19
	v_pk_mul_f32 v[2:3], v[2:3], v[16:17] op_sel_hi:[1,0]
	v_mov_b32_e32 v16, v52
	v_mov_b32_e32 v17, v36
	v_mov_b32_e32 v36, v53
	v_pk_mul_f32 v[16:17], v[16:17], v[18:19] op_sel_hi:[1,0]
	v_pk_mul_f32 v[18:19], v[32:33], v[18:19] op_sel_hi:[1,0]
	v_pk_mul_f32 v[32:33], v[36:37], v[20:21] op_sel_hi:[1,0]
	v_mov_b32_e32 v20, v54
	v_mov_b32_e32 v21, v38
	v_pk_mul_f32 v[48:49], v[20:21], v[4:5] op_sel_hi:[1,0]
	v_mov_b32_e32 v20, v22
	v_mov_b32_e32 v21, v6
	v_pk_mul_f32 v[50:51], v[20:21], v[4:5] op_sel_hi:[1,0]
	v_rcp_f32_e32 v20, v81
	v_mov_b32_e32 v36, v24
	s_waitcnt lgkmcnt(0)
	v_rcp_f32_e32 v24, v77
	v_mov_b32_e32 v38, v55
	v_rcp_f32_e32 v22, v76
	v_mov_b32_e32 v37, v8
	v_mov_b32_e32 v8, v25
	v_pk_mul_f32 v[4:5], v[38:39], v[20:21] op_sel_hi:[1,0]
	v_pk_mul_f32 v[38:39], v[8:9], v[24:25] op_sel_hi:[1,0]
	v_rcp_f32_e32 v8, v78
	v_mov_b32_e32 v6, v23
	v_pk_mul_f32 v[6:7], v[6:7], v[20:21] op_sel_hi:[1,0]
	v_mov_b32_e32 v20, v56
	v_mov_b32_e32 v21, v40
	v_mov_b32_e32 v40, v57
	v_pk_mul_f32 v[20:21], v[20:21], v[22:23] op_sel_hi:[1,0]
	v_pk_mul_f32 v[22:23], v[36:37], v[22:23] op_sel_hi:[1,0]
	v_pk_mul_f32 v[36:37], v[40:41], v[24:25] op_sel_hi:[1,0]
	v_mov_b32_e32 v24, v58
	v_mov_b32_e32 v25, v42
	v_pk_mul_f32 v[52:53], v[24:25], v[8:9] op_sel_hi:[1,0]
	v_mov_b32_e32 v24, v26
	v_mov_b32_e32 v25, v10
	v_pk_mul_f32 v[54:55], v[24:25], v[8:9] op_sel_hi:[1,0]
	v_rcp_f32_e32 v24, v79
	ds_read_b128 v[76:79], v82 offset:49248
	v_mov_b32_e32 v40, v28
	v_mov_b32_e32 v42, v59
	v_mov_b32_e32 v41, v12
	v_mov_b32_e32 v12, v29
	s_waitcnt lgkmcnt(0)
	v_rcp_f32_e32 v28, v77
	v_rcp_f32_e32 v26, v76
	v_pk_mul_f32 v[8:9], v[42:43], v[24:25] op_sel_hi:[1,0]
	v_mov_b32_e32 v10, v27
	v_pk_mul_f32 v[42:43], v[12:13], v[28:29] op_sel_hi:[1,0]
	v_rcp_f32_e32 v12, v78
	v_pk_mul_f32 v[10:11], v[10:11], v[24:25] op_sel_hi:[1,0]
	v_mov_b32_e32 v24, v60
	v_mov_b32_e32 v25, v44
	v_mov_b32_e32 v44, v61
	v_pk_mul_f32 v[24:25], v[24:25], v[26:27] op_sel_hi:[1,0]
	v_pk_mul_f32 v[26:27], v[40:41], v[26:27] op_sel_hi:[1,0]
	v_pk_mul_f32 v[40:41], v[44:45], v[28:29] op_sel_hi:[1,0]
	v_mov_b32_e32 v28, v62
	v_mov_b32_e32 v29, v46
	v_pk_mul_f32 v[56:57], v[28:29], v[12:13] op_sel_hi:[1,0]
	v_mov_b32_e32 v28, v30
	v_mov_b32_e32 v29, v14
	v_pk_mul_f32 v[58:59], v[28:29], v[12:13] op_sel_hi:[1,0]
	v_rcp_f32_e32 v28, v79
	v_mov_b32_e32 v46, v63
	v_mov_b32_e32 v14, v31
	s_mov_b64 s[12:13], -1
	v_pk_mul_f32 v[12:13], v[46:47], v[28:29] op_sel_hi:[1,0]
	v_pk_mul_f32 v[14:15], v[14:15], v[28:29] op_sel_hi:[1,0]
	v_mov_b64_e32 v[28:29], v[154:155]
	s_and_b64 vcc, exec, s[94:95]
	s_barrier
	s_cbranch_vccz .LBB0_191
; __device__ __forceinline__ unsigned cvt_pk_bf16(float lo, float hi) { unsigned r; asm volatile("v_cvt_pk_bf16_f32 %0, %1, %2" : "=v"(r) : "v"(lo), "v"(hi)); return r; }
; __device__ __forceinline__ void phase_attn_diff(const Params& p, char* lds) {
;     ...
;             } else {
;                 bf16_t* Ow = O + (size_t)(row0 + wid * 32 + 4 * hi) * 1024 + h * 128 + r32;
;                 asm volatile("" : "+v"(Ow));
; #pragma unroll
;                 for (int r = 0; r < 16; ++r) {
;                     const f32x4 t = *(const f32x4*)(scr + 4 * r);
;                     const float v0 = t[0] - lam * o[0][r], v1 = t[1] - lam * o[1][r], v2 = t[2] - lam * o[2][r], v3 = t[3] - lam * o[3][r];
;                     float ss = v0 * v0 + v1 * v1 + v2 * v2 + v3 * v3;
; #pragma unroll
;                     for (int x = 16; x >= 1; x >>= 1) ss += __shfl_xor(ss, x);
;                     const float rs = rsqrtf(ss * (1.0f / 128.0f) + EPS);
;                     bf16_t* Or = Ow + (size_t)((r & 3) + 8 * (r >> 2)) * 1024;
;                     Or[0] = (bf16_t)(cvt_pk_bf16(v0 * rs * gs[0], 0.f) & 0xffffu); Or[32] = (bf16_t)(cvt_pk_bf16(v1 * rs * gs[1], 0.f) & 0xffffu);
;                     Or[64] = (bf16_t)(cvt_pk_bf16(v2 * rs * gs[2], 0.f) & 0xffffu); Or[96] = (bf16_t)(cvt_pk_bf16(v3 * rs * gs[3], 0.f) & 0xffffu);
;                 }
	global_load_dwordx4 v[84:87], v[28:29], off
	global_load_dwordx4 v[88:91], v[28:29], off offset:16
	global_load_dwordx4 v[92:95], v[28:29], off offset:32
	global_load_dwordx4 v[100:103], v[28:29], off offset:48
	global_load_dwordx4 v[104:107], v[28:29], off offset:64
	global_load_dwordx4 v[108:111], v[28:29], off offset:80
	global_load_dwordx4 v[112:115], v[28:29], off offset:96
	global_load_dwordx4 v[116:119], v[28:29], off offset:112
	global_load_dwordx4 v[120:123], v[28:29], off offset:128
	global_load_dwordx4 v[124:127], v[28:29], off offset:144
	global_load_dwordx4 v[128:131], v[28:29], off offset:160
	global_load_dwordx4 v[132:135], v[28:29], off offset:176
	global_load_dwordx4 v[136:139], v[28:29], off offset:192
	global_load_dwordx4 v[140:143], v[28:29], off offset:208
	global_load_dwordx4 v[144:147], v[28:29], off offset:224
	global_load_dwordx4 v[148:151], v[28:29], off offset:240
	v_mov_b64_e32 v[30:31], v[162:163]
	v_and_b32_e32 v44, 64, v183
	v_add_u32_e32 v60, 64, v44
	s_mov_b32 s2, 0xd000
	s_waitcnt vmcnt(0) lgkmcnt(0)
	v_pk_fma_f32 v[62:63], v[156:157], v[64:65], v[84:85] neg_lo:[1,0,0] neg_hi:[1,0,0]
	s_nop 0
	v_pk_mul_f32 v[44:45], v[62:63], v[62:63]
	v_pk_fma_f32 v[76:77], v[156:157], v[66:67], v[86:87] neg_lo:[1,0,0] neg_hi:[1,0,0]
	v_add_f32_e32 v44, v44, v45
	v_pk_mul_f32 v[46:47], v[76:77], v[76:77]
	s_nop 0
	v_add_f32_e32 v44, v46, v44
	v_add_f32_e32 v45, v47, v44
	v_xor_b32_e32 v44, 16, v183
	v_cmp_lt_i32_e32 vcc, v44, v60
	s_nop 1
	v_cndmask_b32_e32 v44, v183, v44, vcc
	v_lshlrev_b32_e32 v44, 2, v44
	ds_bpermute_b32 v46, v44, v45
	s_waitcnt lgkmcnt(0)
	v_add_f32_e32 v46, v45, v46
	v_xor_b32_e32 v45, 8, v183
	v_cmp_lt_i32_e32 vcc, v45, v60
	s_nop 1
	v_cndmask_b32_e32 v45, v183, v45, vcc
	v_lshlrev_b32_e32 v45, 2, v45
	ds_bpermute_b32 v47, v45, v46
	s_waitcnt lgkmcnt(0)
	v_add_f32_e32 v47, v46, v47
	v_xor_b32_e32 v46, 4, v183
	v_cmp_lt_i32_e32 vcc, v46, v60
	s_nop 1
	v_cndmask_b32_e32 v46, v183, v46, vcc
	v_lshlrev_b32_e32 v46, 2, v46
	ds_bpermute_b32 v61, v46, v47
	s_waitcnt lgkmcnt(0)
	v_add_f32_e32 v61, v47, v61
	v_xor_b32_e32 v47, 2, v183
	v_cmp_lt_i32_e32 vcc, v47, v60
	s_nop 1
	v_cndmask_b32_e32 v47, v183, v47, vcc
	v_lshlrev_b32_e32 v47, 2, v47
	ds_bpermute_b32 v78, v47, v61
	s_waitcnt lgkmcnt(0)
	v_add_f32_e32 v61, v61, v78
	v_xor_b32_e32 v78, 1, v183
	v_cmp_lt_i32_e32 vcc, v78, v60
	s_nop 1
	v_cndmask_b32_e32 v60, v183, v78, vcc
	v_lshlrev_b32_e32 v60, 2, v60
	ds_bpermute_b32 v78, v60, v61
	s_waitcnt lgkmcnt(0)
	v_add_f32_e32 v61, v61, v78
	v_fmamk_f32 v61, v61, 0x3c000000, v158
	v_cmp_gt_f32_e32 vcc, s82, v61
	v_mul_f32_e32 v78, 0x4b800000, v61
	s_nop 0
	v_cndmask_b32_e32 v61, v61, v78, vcc
	v_rsq_f32_e32 v61, v61
	s_nop 0
	v_mul_f32_e32 v78, 0x45800000, v61
	v_cndmask_b32_e32 v61, v61, v78, vcc
	v_mul_f32_e32 v62, v62, v61
	v_mul_f32_e32 v62, v172, v62
	v_cvt_pk_bf16_f32 v62, v62, v97
	global_store_short v[30:31], v62, off
	v_mul_f32_e32 v62, v63, v61
	v_mul_f32_e32 v62, v173, v62
	v_cvt_pk_bf16_f32 v62, v62, v97
	global_store_short v[30:31], v62, off offset:64
	v_mul_f32_e32 v62, v76, v61
	v_mul_f32_e32 v61, v77, v61
	v_mul_f32_e32 v62, v174, v62
	v_mul_f32_e32 v61, v175, v61
	v_cvt_pk_bf16_f32 v62, v62, v97
	global_store_short v[30:31], v62, off offset:128
	v_cvt_pk_bf16_f32 v61, v61, v97
	global_store_short v[30:31], v61, off offset:192
	s_nop 0
	v_pk_fma_f32 v[62:63], v[156:157], v[68:69], v[88:89] neg_lo:[1,0,0] neg_hi:[1,0,0]
	s_nop 0
	v_pk_mul_f32 v[76:77], v[62:63], v[62:63]
	v_pk_fma_f32 v[78:79], v[156:157], v[70:71], v[90:91] neg_lo:[1,0,0] neg_hi:[1,0,0]
	v_add_f32_e32 v61, v76, v77
	v_pk_mul_f32 v[80:81], v[78:79], v[78:79]
	s_nop 0
	v_add_f32_e32 v61, v80, v61
	v_add_f32_e32 v61, v81, v61
	ds_bpermute_b32 v76, v44, v61
	s_waitcnt lgkmcnt(0)
	v_add_f32_e32 v61, v61, v76
	ds_bpermute_b32 v76, v45, v61
	s_waitcnt lgkmcnt(0)
	v_add_f32_e32 v61, v61, v76
	ds_bpermute_b32 v76, v46, v61
	s_waitcnt lgkmcnt(0)
	v_add_f32_e32 v61, v61, v76
	ds_bpermute_b32 v76, v47, v61
	s_waitcnt lgkmcnt(0)
	v_add_f32_e32 v61, v61, v76
	ds_bpermute_b32 v76, v60, v61
	s_waitcnt lgkmcnt(0)
	v_add_f32_e32 v61, v61, v76
	v_fmamk_f32 v61, v61, 0x3c000000, v158
	v_cmp_gt_f32_e32 vcc, s82, v61
	v_mul_f32_e32 v76, 0x4b800000, v61
	s_nop 0
	v_cndmask_b32_e32 v61, v61, v76, vcc
	v_rsq_f32_e32 v61, v61
	s_nop 0
	v_mul_f32_e32 v76, 0x45800000, v61
	v_cndmask_b32_e32 v61, v61, v76, vcc
	v_mul_f32_e32 v62, v62, v61
	v_mul_f32_e32 v62, v172, v62
	v_cvt_pk_bf16_f32 v62, v62, v97
	global_store_short v[30:31], v62, off offset:2048
	v_mul_f32_e32 v62, v63, v61
	v_mul_f32_e32 v62, v173, v62
	v_cvt_pk_bf16_f32 v62, v62, v97
	global_store_short v[30:31], v62, off offset:2112
	v_mul_f32_e32 v62, v78, v61
	v_mul_f32_e32 v61, v79, v61
	v_mul_f32_e32 v62, v174, v62
	v_mul_f32_e32 v61, v175, v61
	v_cvt_pk_bf16_f32 v62, v62, v97
	global_store_short v[30:31], v62, off offset:2176
	v_cvt_pk_bf16_f32 v61, v61, v97
	global_store_short v[30:31], v61, off offset:2240
	s_nop 0
	v_pk_fma_f32 v[62:63], v[156:157], v[72:73], v[92:93] neg_lo:[1,0,0] neg_hi:[1,0,0]
	s_nop 0
	v_pk_mul_f32 v[76:77], v[62:63], v[62:63]
	v_pk_fma_f32 v[78:79], v[156:157], v[74:75], v[94:95] neg_lo:[1,0,0] neg_hi:[1,0,0]
	v_add_f32_e32 v61, v76, v77
	v_pk_mul_f32 v[80:81], v[78:79], v[78:79]
	s_nop 0
	v_add_f32_e32 v61, v80, v61
	v_add_f32_e32 v61, v81, v61
	ds_bpermute_b32 v76, v44, v61
	s_waitcnt lgkmcnt(0)
	v_add_f32_e32 v61, v61, v76
	ds_bpermute_b32 v76, v45, v61
	s_waitcnt lgkmcnt(0)
	v_add_f32_e32 v61, v61, v76
	ds_bpermute_b32 v76, v46, v61
	s_waitcnt lgkmcnt(0)
	v_add_f32_e32 v61, v61, v76
	ds_bpermute_b32 v76, v47, v61
	s_waitcnt lgkmcnt(0)
; __device__ __forceinline__ unsigned cvt_pk_bf16(float lo, float hi) { unsigned r; asm volatile("v_cvt_pk_bf16_f32 %0, %1, %2" : "=v"(r) : "v"(lo), "v"(hi)); return r; }
; __device__ __forceinline__ void phase_attn_diff(const Params& p, char* lds) {
;     ...
;                 for (int r = 0; r < 16; ++r) {
;                     const f32x4 t = *(const f32x4*)(scr + 4 * r);
;                     const float v0 = t[0] - lam * o[0][r], v1 = t[1] - lam * o[1][r], v2 = t[2] - lam * o[2][r], v3 = t[3] - lam * o[3][r];
;                     float ss = v0 * v0 + v1 * v1 + v2 * v2 + v3 * v3;
; #pragma unroll
;                     for (int x = 16; x >= 1; x >>= 1) ss += __shfl_xor(ss, x);
;                     const float rs = rsqrtf(ss * (1.0f / 128.0f) + EPS);
;                     bf16_t* Or = Ow + (size_t)((r & 3) + 8 * (r >> 2)) * 1024;
;                     Or[0] = (bf16_t)(cvt_pk_bf16(v0 * rs * gs[0], 0.f) & 0xffffu); Or[32] = (bf16_t)(cvt_pk_bf16(v1 * rs * gs[1], 0.f) & 0xffffu);
;                     Or[64] = (bf16_t)(cvt_pk_bf16(v2 * rs * gs[2], 0.f) & 0xffffu); Or[96] = (bf16_t)(cvt_pk_bf16(v3 * rs * gs[3], 0.f) & 0xffffu);
;                 }
	v_add_f32_e32 v61, v61, v76
	ds_bpermute_b32 v76, v60, v61
	s_waitcnt lgkmcnt(0)
	v_add_f32_e32 v61, v61, v76
	v_fmamk_f32 v61, v61, 0x3c000000, v158
	v_cmp_gt_f32_e32 vcc, s82, v61
	v_mul_f32_e32 v76, 0x4b800000, v61
	s_nop 0
	v_cndmask_b32_e32 v61, v61, v76, vcc
	v_rsq_f32_e32 v61, v61
	s_nop 0
	v_mul_f32_e32 v76, 0x45800000, v61
	v_cndmask_b32_e32 v61, v61, v76, vcc
	v_mul_f32_e32 v62, v62, v61
	v_mul_f32_e32 v62, v172, v62
	v_add_co_u32_e32 v80, vcc, s83, v30
	v_cvt_pk_bf16_f32 v62, v62, v97
	s_nop 1
	v_addc_co_u32_e32 v81, vcc, 0, v31, vcc
	global_store_short v[80:81], v62, off
	v_mul_f32_e32 v62, v63, v61
	v_mul_f32_e32 v62, v173, v62
	v_cvt_pk_bf16_f32 v62, v62, v97
	global_store_short v[80:81], v62, off offset:64
	v_mul_f32_e32 v62, v78, v61
	v_mul_f32_e32 v61, v79, v61
	v_mul_f32_e32 v62, v174, v62
	v_mul_f32_e32 v61, v175, v61
	v_cvt_pk_bf16_f32 v62, v62, v97
	global_store_short v[80:81], v62, off offset:128
	v_cvt_pk_bf16_f32 v61, v61, v97
	global_store_short v[80:81], v61, off offset:192
	s_nop 0
	v_pk_fma_f32 v[62:63], v[156:157], v[0:1], v[100:101] neg_lo:[1,0,0] neg_hi:[1,0,0]
	s_nop 0
	v_pk_mul_f32 v[76:77], v[62:63], v[62:63]
	v_pk_fma_f32 v[78:79], v[156:157], v[2:3], v[102:103] neg_lo:[1,0,0] neg_hi:[1,0,0]
	v_add_f32_e32 v61, v76, v77
	v_pk_mul_f32 v[82:83], v[78:79], v[78:79]
	s_nop 0
	v_add_f32_e32 v61, v82, v61
	v_add_f32_e32 v61, v83, v61
	ds_bpermute_b32 v76, v44, v61
	s_waitcnt lgkmcnt(0)
	v_add_f32_e32 v61, v61, v76
	ds_bpermute_b32 v76, v45, v61
	s_waitcnt lgkmcnt(0)
	v_add_f32_e32 v61, v61, v76
	ds_bpermute_b32 v76, v46, v61
	s_waitcnt lgkmcnt(0)
	v_add_f32_e32 v61, v61, v76
	ds_bpermute_b32 v76, v47, v61
	s_waitcnt lgkmcnt(0)
	v_add_f32_e32 v61, v61, v76
	ds_bpermute_b32 v76, v60, v61
	s_waitcnt lgkmcnt(0)
	v_add_f32_e32 v61, v61, v76
	v_fmamk_f32 v61, v61, 0x3c000000, v158
	v_cmp_gt_f32_e32 vcc, s82, v61
	v_mul_f32_e32 v76, 0x4b800000, v61
	s_nop 0
	v_cndmask_b32_e32 v61, v61, v76, vcc
	v_rsq_f32_e32 v61, v61
	s_nop 0
	v_mul_f32_e32 v76, 0x45800000, v61
	v_cndmask_b32_e32 v61, v61, v76, vcc
	v_mul_f32_e32 v62, v62, v61
	v_mul_f32_e32 v62, v172, v62
	v_cvt_pk_bf16_f32 v62, v62, v97
	global_store_short v[80:81], v62, off offset:2048
	v_mul_f32_e32 v62, v63, v61
	v_mul_f32_e32 v62, v173, v62
	v_cvt_pk_bf16_f32 v62, v62, v97
	global_store_short v[80:81], v62, off offset:2112
	v_mul_f32_e32 v62, v78, v61
	v_mul_f32_e32 v61, v79, v61
	v_mul_f32_e32 v62, v174, v62
	v_mul_f32_e32 v61, v175, v61
	v_cvt_pk_bf16_f32 v62, v62, v97
	global_store_short v[80:81], v62, off offset:2176
	v_cvt_pk_bf16_f32 v61, v61, v97
	global_store_short v[80:81], v61, off offset:2240
	s_nop 0
	v_pk_fma_f32 v[62:63], v[156:157], v[16:17], v[104:105] neg_lo:[1,0,0] neg_hi:[1,0,0]
	s_nop 0
	v_pk_mul_f32 v[76:77], v[62:63], v[62:63]
	v_pk_fma_f32 v[78:79], v[156:157], v[18:19], v[106:107] neg_lo:[1,0,0] neg_hi:[1,0,0]
	v_add_f32_e32 v61, v76, v77
	v_pk_mul_f32 v[80:81], v[78:79], v[78:79]
	s_nop 0
	v_add_f32_e32 v61, v80, v61
	v_add_f32_e32 v61, v81, v61
	ds_bpermute_b32 v76, v44, v61
	s_waitcnt lgkmcnt(0)
	v_add_f32_e32 v61, v61, v76
	ds_bpermute_b32 v76, v45, v61
	s_waitcnt lgkmcnt(0)
	v_add_f32_e32 v61, v61, v76
	ds_bpermute_b32 v76, v46, v61
	s_waitcnt lgkmcnt(0)
	v_add_f32_e32 v61, v61, v76
	ds_bpermute_b32 v76, v47, v61
	s_waitcnt lgkmcnt(0)
	v_add_f32_e32 v61, v61, v76
	ds_bpermute_b32 v76, v60, v61
	s_waitcnt lgkmcnt(0)
	v_add_f32_e32 v61, v61, v76
	v_fmamk_f32 v61, v61, 0x3c000000, v158
	v_cmp_gt_f32_e32 vcc, s82, v61
	v_mul_f32_e32 v76, 0x4b800000, v61
	s_nop 0
	v_cndmask_b32_e32 v61, v61, v76, vcc
	v_rsq_f32_e32 v61, v61
	s_nop 0
	v_mul_f32_e32 v76, 0x45800000, v61
	v_cndmask_b32_e32 v61, v61, v76, vcc
	v_mul_f32_e32 v62, v62, v61
	v_mul_f32_e32 v62, v172, v62
	v_add_co_u32_e32 v80, vcc, s54, v30
	v_cvt_pk_bf16_f32 v62, v62, v97
	s_nop 1
	v_addc_co_u32_e32 v81, vcc, 0, v31, vcc
	global_store_short v[80:81], v62, off
	v_mul_f32_e32 v62, v63, v61
	v_mul_f32_e32 v62, v173, v62
	v_cvt_pk_bf16_f32 v62, v62, v97
	global_store_short v[80:81], v62, off offset:64
	v_mul_f32_e32 v62, v78, v61
	v_mul_f32_e32 v61, v79, v61
	v_mul_f32_e32 v62, v174, v62
	v_mul_f32_e32 v61, v175, v61
	v_cvt_pk_bf16_f32 v62, v62, v97
	global_store_short v[80:81], v62, off offset:128
	v_cvt_pk_bf16_f32 v61, v61, v97
	global_store_short v[80:81], v61, off offset:192
	s_nop 0
	v_pk_fma_f32 v[62:63], v[156:157], v[32:33], v[108:109] neg_lo:[1,0,0] neg_hi:[1,0,0]
	s_nop 0
	v_pk_mul_f32 v[76:77], v[62:63], v[62:63]
	v_pk_fma_f32 v[78:79], v[156:157], v[34:35], v[110:111] neg_lo:[1,0,0] neg_hi:[1,0,0]
	v_add_f32_e32 v61, v76, v77
	v_pk_mul_f32 v[82:83], v[78:79], v[78:79]
	s_nop 0
	v_add_f32_e32 v61, v82, v61
	v_add_f32_e32 v61, v83, v61
	ds_bpermute_b32 v76, v44, v61
	s_waitcnt lgkmcnt(0)
	v_add_f32_e32 v61, v61, v76
	ds_bpermute_b32 v76, v45, v61
	s_waitcnt lgkmcnt(0)
	v_add_f32_e32 v61, v61, v76
	ds_bpermute_b32 v76, v46, v61
	s_waitcnt lgkmcnt(0)
	v_add_f32_e32 v61, v61, v76
	ds_bpermute_b32 v76, v47, v61
	s_waitcnt lgkmcnt(0)
	v_add_f32_e32 v61, v61, v76
	ds_bpermute_b32 v76, v60, v61
	s_waitcnt lgkmcnt(0)
; __device__ __forceinline__ unsigned cvt_pk_bf16(float lo, float hi) { unsigned r; asm volatile("v_cvt_pk_bf16_f32 %0, %1, %2" : "=v"(r) : "v"(lo), "v"(hi)); return r; }
; __device__ __forceinline__ void phase_attn_diff(const Params& p, char* lds) {
;     ...
;                 for (int r = 0; r < 16; ++r) {
;                     const f32x4 t = *(const f32x4*)(scr + 4 * r);
;                     const float v0 = t[0] - lam * o[0][r], v1 = t[1] - lam * o[1][r], v2 = t[2] - lam * o[2][r], v3 = t[3] - lam * o[3][r];
;                     float ss = v0 * v0 + v1 * v1 + v2 * v2 + v3 * v3;
; #pragma unroll
;                     for (int x = 16; x >= 1; x >>= 1) ss += __shfl_xor(ss, x);
;                     const float rs = rsqrtf(ss * (1.0f / 128.0f) + EPS);
;                     bf16_t* Or = Ow + (size_t)((r & 3) + 8 * (r >> 2)) * 1024;
;                     Or[0] = (bf16_t)(cvt_pk_bf16(v0 * rs * gs[0], 0.f) & 0xffffu); Or[32] = (bf16_t)(cvt_pk_bf16(v1 * rs * gs[1], 0.f) & 0xffffu);
;                     Or[64] = (bf16_t)(cvt_pk_bf16(v2 * rs * gs[2], 0.f) & 0xffffu); Or[96] = (bf16_t)(cvt_pk_bf16(v3 * rs * gs[3], 0.f) & 0xffffu);
;                 }
	v_add_f32_e32 v61, v61, v76
	v_fmamk_f32 v61, v61, 0x3c000000, v158
	v_cmp_gt_f32_e32 vcc, s82, v61
	v_mul_f32_e32 v76, 0x4b800000, v61
	s_nop 0
	v_cndmask_b32_e32 v61, v61, v76, vcc
	v_rsq_f32_e32 v61, v61
	s_nop 0
	v_mul_f32_e32 v76, 0x45800000, v61
	v_cndmask_b32_e32 v61, v61, v76, vcc
	v_mul_f32_e32 v62, v62, v61
	v_mul_f32_e32 v62, v172, v62
	v_cvt_pk_bf16_f32 v62, v62, v97
	global_store_short v[80:81], v62, off offset:2048
	v_mul_f32_e32 v62, v63, v61
	v_mul_f32_e32 v62, v173, v62
	v_cvt_pk_bf16_f32 v62, v62, v97
	global_store_short v[80:81], v62, off offset:2112
	v_mul_f32_e32 v62, v78, v61
	v_mul_f32_e32 v61, v79, v61
	v_mul_f32_e32 v62, v174, v62
	v_mul_f32_e32 v61, v175, v61
	v_cvt_pk_bf16_f32 v62, v62, v97
	global_store_short v[80:81], v62, off offset:2176
	v_cvt_pk_bf16_f32 v61, v61, v97
	global_store_short v[80:81], v61, off offset:2240
	s_nop 0
	v_pk_fma_f32 v[62:63], v[156:157], v[48:49], v[112:113] neg_lo:[1,0,0] neg_hi:[1,0,0]
	s_nop 0
	v_pk_mul_f32 v[76:77], v[62:63], v[62:63]
	v_pk_fma_f32 v[78:79], v[156:157], v[50:51], v[114:115] neg_lo:[1,0,0] neg_hi:[1,0,0]
	v_add_f32_e32 v61, v76, v77
	v_pk_mul_f32 v[80:81], v[78:79], v[78:79]
	s_nop 0
	v_add_f32_e32 v61, v80, v61
	v_add_f32_e32 v61, v81, v61
	ds_bpermute_b32 v76, v44, v61
	s_waitcnt lgkmcnt(0)
	v_add_f32_e32 v61, v61, v76
	ds_bpermute_b32 v76, v45, v61
	s_waitcnt lgkmcnt(0)
	v_add_f32_e32 v61, v61, v76
	ds_bpermute_b32 v76, v46, v61
	s_waitcnt lgkmcnt(0)
	v_add_f32_e32 v61, v61, v76
	ds_bpermute_b32 v76, v47, v61
	s_waitcnt lgkmcnt(0)
	v_add_f32_e32 v61, v61, v76
	ds_bpermute_b32 v76, v60, v61
	s_waitcnt lgkmcnt(0)
	v_add_f32_e32 v61, v61, v76
	v_fmamk_f32 v61, v61, 0x3c000000, v158
	v_cmp_gt_f32_e32 vcc, s82, v61
	v_mul_f32_e32 v76, 0x4b800000, v61
	s_nop 0
	v_cndmask_b32_e32 v61, v61, v76, vcc
	v_rsq_f32_e32 v61, v61
	s_nop 0
	v_mul_f32_e32 v76, 0x45800000, v61
	v_cndmask_b32_e32 v61, v61, v76, vcc
	v_mul_f32_e32 v62, v62, v61
	v_mul_f32_e32 v62, v172, v62
	v_add_co_u32_e32 v80, vcc, s59, v30
	v_cvt_pk_bf16_f32 v62, v62, v97
	s_nop 1
	v_addc_co_u32_e32 v81, vcc, 0, v31, vcc
	global_store_short v[80:81], v62, off
	v_mul_f32_e32 v62, v63, v61
	v_mul_f32_e32 v62, v173, v62
	v_cvt_pk_bf16_f32 v62, v62, v97
	global_store_short v[80:81], v62, off offset:64
	v_mul_f32_e32 v62, v78, v61
	v_mul_f32_e32 v61, v79, v61
	v_mul_f32_e32 v62, v174, v62
	v_mul_f32_e32 v61, v175, v61
	v_cvt_pk_bf16_f32 v62, v62, v97
	global_store_short v[80:81], v62, off offset:128
	v_cvt_pk_bf16_f32 v61, v61, v97
	global_store_short v[80:81], v61, off offset:192
	s_nop 0
	v_pk_fma_f32 v[62:63], v[156:157], v[4:5], v[116:117] neg_lo:[1,0,0] neg_hi:[1,0,0]
	s_nop 0
	v_pk_mul_f32 v[76:77], v[62:63], v[62:63]
	v_pk_fma_f32 v[78:79], v[156:157], v[6:7], v[118:119] neg_lo:[1,0,0] neg_hi:[1,0,0]
	v_add_f32_e32 v61, v76, v77
	v_pk_mul_f32 v[82:83], v[78:79], v[78:79]
	s_nop 0
	v_add_f32_e32 v61, v82, v61
	v_add_f32_e32 v61, v83, v61
	ds_bpermute_b32 v76, v44, v61
	s_waitcnt lgkmcnt(0)
	v_add_f32_e32 v61, v61, v76
	ds_bpermute_b32 v76, v45, v61
	s_waitcnt lgkmcnt(0)
	v_add_f32_e32 v61, v61, v76
	ds_bpermute_b32 v76, v46, v61
	s_waitcnt lgkmcnt(0)
	v_add_f32_e32 v61, v61, v76
	ds_bpermute_b32 v76, v47, v61
	s_waitcnt lgkmcnt(0)
	v_add_f32_e32 v61, v61, v76
	ds_bpermute_b32 v76, v60, v61
	s_waitcnt lgkmcnt(0)
	v_add_f32_e32 v61, v61, v76
	v_fmamk_f32 v61, v61, 0x3c000000, v158
	v_cmp_gt_f32_e32 vcc, s82, v61
	v_mul_f32_e32 v76, 0x4b800000, v61
	s_nop 0
	v_cndmask_b32_e32 v61, v61, v76, vcc
	v_rsq_f32_e32 v61, v61
	s_nop 0
	v_mul_f32_e32 v76, 0x45800000, v61
	v_cndmask_b32_e32 v61, v61, v76, vcc
	v_mul_f32_e32 v62, v62, v61
	v_mul_f32_e32 v62, v172, v62
	v_cvt_pk_bf16_f32 v62, v62, v97
	global_store_short v[80:81], v62, off offset:2048
	v_mul_f32_e32 v62, v63, v61
	v_mul_f32_e32 v62, v173, v62
	v_cvt_pk_bf16_f32 v62, v62, v97
	global_store_short v[80:81], v62, off offset:2112
	v_mul_f32_e32 v62, v78, v61
	v_mul_f32_e32 v61, v79, v61
	v_mul_f32_e32 v62, v174, v62
	v_mul_f32_e32 v61, v175, v61
	v_cvt_pk_bf16_f32 v62, v62, v97
	global_store_short v[80:81], v62, off offset:2176
	v_cvt_pk_bf16_f32 v61, v61, v97
	global_store_short v[80:81], v61, off offset:2240
	s_nop 0
	v_pk_fma_f32 v[62:63], v[156:157], v[20:21], v[120:121] neg_lo:[1,0,0] neg_hi:[1,0,0]
	s_nop 0
	v_pk_mul_f32 v[76:77], v[62:63], v[62:63]
	v_pk_fma_f32 v[78:79], v[156:157], v[22:23], v[122:123] neg_lo:[1,0,0] neg_hi:[1,0,0]
	v_add_f32_e32 v61, v76, v77
	v_pk_mul_f32 v[80:81], v[78:79], v[78:79]
	s_nop 0
	v_add_f32_e32 v61, v80, v61
	v_add_f32_e32 v61, v81, v61
	ds_bpermute_b32 v76, v44, v61
	s_waitcnt lgkmcnt(0)
	v_add_f32_e32 v61, v61, v76
	ds_bpermute_b32 v76, v45, v61
	s_waitcnt lgkmcnt(0)
	v_add_f32_e32 v61, v61, v76
	ds_bpermute_b32 v76, v46, v61
	s_waitcnt lgkmcnt(0)
	v_add_f32_e32 v61, v61, v76
	ds_bpermute_b32 v76, v47, v61
	s_waitcnt lgkmcnt(0)
	v_add_f32_e32 v61, v61, v76
	ds_bpermute_b32 v76, v60, v61
	s_waitcnt lgkmcnt(0)
	v_add_f32_e32 v61, v61, v76
	v_fmamk_f32 v61, v61, 0x3c000000, v158
	v_cmp_gt_f32_e32 vcc, s82, v61
	v_mul_f32_e32 v76, 0x4b800000, v61
	s_nop 0
	v_cndmask_b32_e32 v61, v61, v76, vcc
	v_rsq_f32_e32 v61, v61
	s_nop 0
	v_mul_f32_e32 v76, 0x45800000, v61
	v_cndmask_b32_e32 v61, v61, v76, vcc
	v_mul_f32_e32 v62, v62, v61
	v_mul_f32_e32 v62, v172, v62
	v_add_co_u32_e32 v80, vcc, s67, v30
	v_cvt_pk_bf16_f32 v62, v62, v97
	s_nop 1
	v_addc_co_u32_e32 v81, vcc, 0, v31, vcc
	global_store_short v[80:81], v62, off
	v_mul_f32_e32 v62, v63, v61
	v_mul_f32_e32 v62, v173, v62
	v_cvt_pk_bf16_f32 v62, v62, v97
	global_store_short v[80:81], v62, off offset:64
	v_mul_f32_e32 v62, v78, v61
	v_mul_f32_e32 v61, v79, v61
	v_mul_f32_e32 v62, v174, v62
	v_mul_f32_e32 v61, v175, v61
	v_cvt_pk_bf16_f32 v62, v62, v97
	global_store_short v[80:81], v62, off offset:128
	v_cvt_pk_bf16_f32 v61, v61, v97
	global_store_short v[80:81], v61, off offset:192
	s_nop 0
	v_pk_fma_f32 v[62:63], v[156:157], v[36:37], v[124:125] neg_lo:[1,0,0] neg_hi:[1,0,0]
	s_nop 0
	v_pk_mul_f32 v[76:77], v[62:63], v[62:63]
	v_pk_fma_f32 v[78:79], v[156:157], v[38:39], v[126:127] neg_lo:[1,0,0] neg_hi:[1,0,0]
	v_add_f32_e32 v61, v76, v77
	v_pk_mul_f32 v[82:83], v[78:79], v[78:79]
	s_nop 0
	v_add_f32_e32 v61, v82, v61
	v_add_f32_e32 v61, v83, v61
	ds_bpermute_b32 v76, v44, v61
	s_waitcnt lgkmcnt(0)
; __device__ __forceinline__ unsigned cvt_pk_bf16(float lo, float hi) { unsigned r; asm volatile("v_cvt_pk_bf16_f32 %0, %1, %2" : "=v"(r) : "v"(lo), "v"(hi)); return r; }
; __device__ __forceinline__ void phase_attn_diff(const Params& p, char* lds) {
;     ...
;                 for (int r = 0; r < 16; ++r) {
;                     const f32x4 t = *(const f32x4*)(scr + 4 * r);
;                     const float v0 = t[0] - lam * o[0][r], v1 = t[1] - lam * o[1][r], v2 = t[2] - lam * o[2][r], v3 = t[3] - lam * o[3][r];
;                     float ss = v0 * v0 + v1 * v1 + v2 * v2 + v3 * v3;
; #pragma unroll
;                     for (int x = 16; x >= 1; x >>= 1) ss += __shfl_xor(ss, x);
;                     const float rs = rsqrtf(ss * (1.0f / 128.0f) + EPS);
;                     bf16_t* Or = Ow + (size_t)((r & 3) + 8 * (r >> 2)) * 1024;
;                     Or[0] = (bf16_t)(cvt_pk_bf16(v0 * rs * gs[0], 0.f) & 0xffffu); Or[32] = (bf16_t)(cvt_pk_bf16(v1 * rs * gs[1], 0.f) & 0xffffu);
;                     Or[64] = (bf16_t)(cvt_pk_bf16(v2 * rs * gs[2], 0.f) & 0xffffu); Or[96] = (bf16_t)(cvt_pk_bf16(v3 * rs * gs[3], 0.f) & 0xffffu);
;                 }
	v_add_f32_e32 v61, v61, v76
	ds_bpermute_b32 v76, v45, v61
	s_waitcnt lgkmcnt(0)
	v_add_f32_e32 v61, v61, v76
	ds_bpermute_b32 v76, v46, v61
	s_waitcnt lgkmcnt(0)
	v_add_f32_e32 v61, v61, v76
	ds_bpermute_b32 v76, v47, v61
	s_waitcnt lgkmcnt(0)
	v_add_f32_e32 v61, v61, v76
	ds_bpermute_b32 v76, v60, v61
	s_waitcnt lgkmcnt(0)
	v_add_f32_e32 v61, v61, v76
	v_fmamk_f32 v61, v61, 0x3c000000, v158
	v_cmp_gt_f32_e32 vcc, s82, v61
	v_mul_f32_e32 v76, 0x4b800000, v61
	s_nop 0
	v_cndmask_b32_e32 v61, v61, v76, vcc
	v_rsq_f32_e32 v61, v61
	s_nop 0
	v_mul_f32_e32 v76, 0x45800000, v61
	v_cndmask_b32_e32 v61, v61, v76, vcc
	v_mul_f32_e32 v62, v62, v61
	v_mul_f32_e32 v62, v172, v62
	v_cvt_pk_bf16_f32 v62, v62, v97
	global_store_short v[80:81], v62, off offset:2048
	v_mul_f32_e32 v62, v63, v61
	v_mul_f32_e32 v62, v173, v62
	v_cvt_pk_bf16_f32 v62, v62, v97
	global_store_short v[80:81], v62, off offset:2112
	v_mul_f32_e32 v62, v78, v61
	v_mul_f32_e32 v61, v79, v61
	v_mul_f32_e32 v62, v174, v62
	v_mul_f32_e32 v61, v175, v61
	v_cvt_pk_bf16_f32 v62, v62, v97
	global_store_short v[80:81], v62, off offset:2176
	v_cvt_pk_bf16_f32 v61, v61, v97
	global_store_short v[80:81], v61, off offset:2240
	s_nop 0
	v_pk_fma_f32 v[62:63], v[156:157], v[52:53], v[128:129] neg_lo:[1,0,0] neg_hi:[1,0,0]
	s_nop 0
	v_pk_mul_f32 v[76:77], v[62:63], v[62:63]
	v_pk_fma_f32 v[78:79], v[156:157], v[54:55], v[130:131] neg_lo:[1,0,0] neg_hi:[1,0,0]
	v_add_f32_e32 v61, v76, v77
	v_pk_mul_f32 v[80:81], v[78:79], v[78:79]
	s_nop 0
	v_add_f32_e32 v61, v80, v61
	v_add_f32_e32 v61, v81, v61
	ds_bpermute_b32 v76, v44, v61
	s_waitcnt lgkmcnt(0)
	v_add_f32_e32 v61, v61, v76
	ds_bpermute_b32 v76, v45, v61
	s_waitcnt lgkmcnt(0)
	v_add_f32_e32 v61, v61, v76
	ds_bpermute_b32 v76, v46, v61
	s_waitcnt lgkmcnt(0)
	v_add_f32_e32 v61, v61, v76
	ds_bpermute_b32 v76, v47, v61
	s_waitcnt lgkmcnt(0)
	v_add_f32_e32 v61, v61, v76
	ds_bpermute_b32 v76, v60, v61
	s_waitcnt lgkmcnt(0)
	v_add_f32_e32 v61, v61, v76
	v_fmamk_f32 v61, v61, 0x3c000000, v158
	v_cmp_gt_f32_e32 vcc, s82, v61
	v_mul_f32_e32 v76, 0x4b800000, v61
	s_nop 0
	v_cndmask_b32_e32 v61, v61, v76, vcc
	v_rsq_f32_e32 v61, v61
	s_nop 0
	v_mul_f32_e32 v76, 0x45800000, v61
	v_cndmask_b32_e32 v61, v61, v76, vcc
	v_mul_f32_e32 v62, v62, v61
	v_mul_f32_e32 v62, v172, v62
	v_add_co_u32_e32 v80, vcc, s55, v30
	v_cvt_pk_bf16_f32 v62, v62, v97
	s_nop 1
	v_addc_co_u32_e32 v81, vcc, 0, v31, vcc
	global_store_short v[80:81], v62, off
	v_mul_f32_e32 v62, v63, v61
	v_mul_f32_e32 v62, v173, v62
	v_cvt_pk_bf16_f32 v62, v62, v97
	global_store_short v[80:81], v62, off offset:64
	v_mul_f32_e32 v62, v78, v61
	v_mul_f32_e32 v61, v79, v61
	v_mul_f32_e32 v62, v174, v62
	v_mul_f32_e32 v61, v175, v61
	v_cvt_pk_bf16_f32 v62, v62, v97
	global_store_short v[80:81], v62, off offset:128
	v_cvt_pk_bf16_f32 v61, v61, v97
	global_store_short v[80:81], v61, off offset:192
	s_nop 0
	v_pk_fma_f32 v[62:63], v[156:157], v[8:9], v[132:133] neg_lo:[1,0,0] neg_hi:[1,0,0]
	s_nop 0
	v_pk_mul_f32 v[76:77], v[62:63], v[62:63]
	v_pk_fma_f32 v[78:79], v[156:157], v[10:11], v[134:135] neg_lo:[1,0,0] neg_hi:[1,0,0]
	v_add_f32_e32 v61, v76, v77
	v_pk_mul_f32 v[82:83], v[78:79], v[78:79]
	s_nop 0
	v_add_f32_e32 v61, v82, v61
	v_add_f32_e32 v61, v83, v61
	ds_bpermute_b32 v76, v44, v61
	s_waitcnt lgkmcnt(0)
	v_add_f32_e32 v61, v61, v76
	ds_bpermute_b32 v76, v45, v61
	s_waitcnt lgkmcnt(0)
	v_add_f32_e32 v61, v61, v76
	ds_bpermute_b32 v76, v46, v61
	s_waitcnt lgkmcnt(0)
	v_add_f32_e32 v61, v61, v76
	ds_bpermute_b32 v76, v47, v61
	s_waitcnt lgkmcnt(0)
	v_add_f32_e32 v61, v61, v76
	ds_bpermute_b32 v76, v60, v61
	s_waitcnt lgkmcnt(0)
	v_add_f32_e32 v61, v61, v76
	v_fmamk_f32 v61, v61, 0x3c000000, v158
	v_cmp_gt_f32_e32 vcc, s82, v61
	v_mul_f32_e32 v76, 0x4b800000, v61
	s_nop 0
	v_cndmask_b32_e32 v61, v61, v76, vcc
	v_rsq_f32_e32 v61, v61
	s_nop 0
	v_mul_f32_e32 v76, 0x45800000, v61
	v_cndmask_b32_e32 v61, v61, v76, vcc
	v_mul_f32_e32 v62, v62, v61
	v_mul_f32_e32 v62, v172, v62
	v_cvt_pk_bf16_f32 v62, v62, v97
	global_store_short v[80:81], v62, off offset:2048
	v_mul_f32_e32 v62, v63, v61
	v_mul_f32_e32 v62, v173, v62
	v_cvt_pk_bf16_f32 v62, v62, v97
	global_store_short v[80:81], v62, off offset:2112
	v_mul_f32_e32 v62, v78, v61
	v_mul_f32_e32 v61, v79, v61
	v_mul_f32_e32 v62, v174, v62
	v_mul_f32_e32 v61, v175, v61
	v_cvt_pk_bf16_f32 v62, v62, v97
	global_store_short v[80:81], v62, off offset:2176
	v_cvt_pk_bf16_f32 v61, v61, v97
	global_store_short v[80:81], v61, off offset:2240
	s_nop 0
	v_pk_fma_f32 v[62:63], v[156:157], v[24:25], v[136:137] neg_lo:[1,0,0] neg_hi:[1,0,0]
	s_nop 0
	v_pk_mul_f32 v[76:77], v[62:63], v[62:63]
	v_pk_fma_f32 v[78:79], v[156:157], v[26:27], v[138:139] neg_lo:[1,0,0] neg_hi:[1,0,0]
	v_add_f32_e32 v61, v76, v77
	v_pk_mul_f32 v[80:81], v[78:79], v[78:79]
	s_nop 0
	v_add_f32_e32 v61, v80, v61
	v_add_f32_e32 v61, v81, v61
	ds_bpermute_b32 v76, v44, v61
	s_waitcnt lgkmcnt(0)
	v_add_f32_e32 v61, v61, v76
	ds_bpermute_b32 v76, v45, v61
	s_waitcnt lgkmcnt(0)
	v_add_f32_e32 v61, v61, v76
	ds_bpermute_b32 v76, v46, v61
	s_waitcnt lgkmcnt(0)
	v_add_f32_e32 v61, v61, v76
	ds_bpermute_b32 v76, v47, v61
	s_waitcnt lgkmcnt(0)
	v_add_f32_e32 v61, v61, v76
	ds_bpermute_b32 v76, v60, v61
	s_waitcnt lgkmcnt(0)
; __device__ __forceinline__ unsigned cvt_pk_bf16(float lo, float hi) { unsigned r; asm volatile("v_cvt_pk_bf16_f32 %0, %1, %2" : "=v"(r) : "v"(lo), "v"(hi)); return r; }
; __device__ __forceinline__ void phase_attn_diff(const Params& p, char* lds) {
;     ...
;                 for (int r = 0; r < 16; ++r) {
;                     const f32x4 t = *(const f32x4*)(scr + 4 * r);
;                     const float v0 = t[0] - lam * o[0][r], v1 = t[1] - lam * o[1][r], v2 = t[2] - lam * o[2][r], v3 = t[3] - lam * o[3][r];
;                     float ss = v0 * v0 + v1 * v1 + v2 * v2 + v3 * v3;
; #pragma unroll
;                     for (int x = 16; x >= 1; x >>= 1) ss += __shfl_xor(ss, x);
;                     const float rs = rsqrtf(ss * (1.0f / 128.0f) + EPS);
;                     bf16_t* Or = Ow + (size_t)((r & 3) + 8 * (r >> 2)) * 1024;
;                     Or[0] = (bf16_t)(cvt_pk_bf16(v0 * rs * gs[0], 0.f) & 0xffffu); Or[32] = (bf16_t)(cvt_pk_bf16(v1 * rs * gs[1], 0.f) & 0xffffu);
;                     Or[64] = (bf16_t)(cvt_pk_bf16(v2 * rs * gs[2], 0.f) & 0xffffu); Or[96] = (bf16_t)(cvt_pk_bf16(v3 * rs * gs[3], 0.f) & 0xffffu);
;                 }
	v_add_f32_e32 v61, v61, v76
	v_fmamk_f32 v61, v61, 0x3c000000, v158
	v_cmp_gt_f32_e32 vcc, s82, v61
	v_mul_f32_e32 v76, 0x4b800000, v61
	s_nop 0
	v_cndmask_b32_e32 v61, v61, v76, vcc
	v_rsq_f32_e32 v61, v61
	s_nop 0
	v_mul_f32_e32 v76, 0x45800000, v61
	v_cndmask_b32_e32 v61, v61, v76, vcc
	v_mul_f32_e32 v62, v62, v61
	v_mul_f32_e32 v62, v172, v62
	v_add_co_u32_e32 v80, vcc, s58, v30
	v_cvt_pk_bf16_f32 v62, v62, v97
	s_nop 1
	v_addc_co_u32_e32 v81, vcc, 0, v31, vcc
	global_store_short v[80:81], v62, off
	v_mul_f32_e32 v62, v63, v61
	v_mul_f32_e32 v62, v173, v62
	v_cvt_pk_bf16_f32 v62, v62, v97
	global_store_short v[80:81], v62, off offset:64
	v_mul_f32_e32 v62, v78, v61
	v_mul_f32_e32 v61, v79, v61
	v_mul_f32_e32 v62, v174, v62
	v_mul_f32_e32 v61, v175, v61
	v_cvt_pk_bf16_f32 v62, v62, v97
	global_store_short v[80:81], v62, off offset:128
	v_cvt_pk_bf16_f32 v61, v61, v97
	global_store_short v[80:81], v61, off offset:192
	s_nop 0
	v_pk_fma_f32 v[62:63], v[156:157], v[40:41], v[140:141] neg_lo:[1,0,0] neg_hi:[1,0,0]
	s_nop 0
	v_pk_mul_f32 v[76:77], v[62:63], v[62:63]
	v_pk_fma_f32 v[78:79], v[156:157], v[42:43], v[142:143] neg_lo:[1,0,0] neg_hi:[1,0,0]
	v_add_f32_e32 v61, v76, v77
	v_pk_mul_f32 v[82:83], v[78:79], v[78:79]
	s_nop 0
	v_add_f32_e32 v61, v82, v61
	v_add_f32_e32 v61, v83, v61
	ds_bpermute_b32 v76, v44, v61
	s_waitcnt lgkmcnt(0)
	v_add_f32_e32 v61, v61, v76
	ds_bpermute_b32 v76, v45, v61
	s_waitcnt lgkmcnt(0)
	v_add_f32_e32 v61, v61, v76
	ds_bpermute_b32 v76, v46, v61
	s_waitcnt lgkmcnt(0)
	v_add_f32_e32 v61, v61, v76
	ds_bpermute_b32 v76, v47, v61
	s_waitcnt lgkmcnt(0)
	v_add_f32_e32 v61, v61, v76
	ds_bpermute_b32 v76, v60, v61
	s_waitcnt lgkmcnt(0)
	v_add_f32_e32 v61, v61, v76
	v_fmamk_f32 v61, v61, 0x3c000000, v158
	v_cmp_gt_f32_e32 vcc, s82, v61
	v_mul_f32_e32 v76, 0x4b800000, v61
	s_nop 0
	v_cndmask_b32_e32 v61, v61, v76, vcc
	v_rsq_f32_e32 v61, v61
	s_nop 0
	v_mul_f32_e32 v76, 0x45800000, v61
	v_cndmask_b32_e32 v61, v61, v76, vcc
	v_mul_f32_e32 v62, v62, v61
	v_mul_f32_e32 v62, v172, v62
	v_cvt_pk_bf16_f32 v62, v62, v97
	global_store_short v[80:81], v62, off offset:2048
	v_mul_f32_e32 v62, v63, v61
	v_mul_f32_e32 v62, v173, v62
	v_cvt_pk_bf16_f32 v62, v62, v97
	global_store_short v[80:81], v62, off offset:2112
	v_mul_f32_e32 v62, v78, v61
	v_mul_f32_e32 v61, v79, v61
	v_mul_f32_e32 v62, v174, v62
	v_mul_f32_e32 v61, v175, v61
	v_cvt_pk_bf16_f32 v62, v62, v97
	global_store_short v[80:81], v62, off offset:2176
	v_cvt_pk_bf16_f32 v61, v61, v97
	global_store_short v[80:81], v61, off offset:2240
	s_nop 0
	v_pk_fma_f32 v[62:63], v[156:157], v[56:57], v[144:145] neg_lo:[1,0,0] neg_hi:[1,0,0]
	s_nop 0
	v_pk_mul_f32 v[76:77], v[62:63], v[62:63]
	v_pk_fma_f32 v[78:79], v[156:157], v[58:59], v[146:147] neg_lo:[1,0,0] neg_hi:[1,0,0]
	v_add_f32_e32 v61, v76, v77
	v_pk_mul_f32 v[80:81], v[78:79], v[78:79]
	s_nop 0
	v_add_f32_e32 v61, v80, v61
	v_add_f32_e32 v61, v81, v61
	ds_bpermute_b32 v76, v44, v61
	s_waitcnt lgkmcnt(0)
	v_add_f32_e32 v61, v61, v76
	ds_bpermute_b32 v76, v45, v61
	s_waitcnt lgkmcnt(0)
	v_add_f32_e32 v61, v61, v76
	ds_bpermute_b32 v76, v46, v61
	s_waitcnt lgkmcnt(0)
	v_add_f32_e32 v61, v61, v76
	ds_bpermute_b32 v76, v47, v61
	s_waitcnt lgkmcnt(0)
	v_add_f32_e32 v61, v61, v76
	ds_bpermute_b32 v76, v60, v61
	s_waitcnt lgkmcnt(0)
	v_add_f32_e32 v61, v61, v76
	v_fmamk_f32 v61, v61, 0x3c000000, v158
	v_cmp_gt_f32_e32 vcc, s82, v61
	v_mul_f32_e32 v76, 0x4b800000, v61
	s_nop 0
	v_cndmask_b32_e32 v61, v61, v76, vcc
	v_rsq_f32_e32 v61, v61
	s_nop 0
	v_mul_f32_e32 v76, 0x45800000, v61
	v_cndmask_b32_e32 v61, v61, v76, vcc
	v_mul_f32_e32 v62, v62, v61
	v_mul_f32_e32 v62, v172, v62
	v_add_co_u32_e32 v30, vcc, s2, v30
	v_cvt_pk_bf16_f32 v62, v62, v97
	s_nop 1
	v_addc_co_u32_e32 v31, vcc, 0, v31, vcc
	global_store_short v[30:31], v62, off
	v_mul_f32_e32 v62, v63, v61
	v_mul_f32_e32 v62, v173, v62
	v_cvt_pk_bf16_f32 v62, v62, v97
	global_store_short v[30:31], v62, off offset:64
	v_mul_f32_e32 v62, v78, v61
	v_mul_f32_e32 v61, v79, v61
	v_mul_f32_e32 v62, v174, v62
	v_mul_f32_e32 v61, v175, v61
	v_cvt_pk_bf16_f32 v62, v62, v97
	global_store_short v[30:31], v62, off offset:128
	v_cvt_pk_bf16_f32 v61, v61, v97
	global_store_short v[30:31], v61, off offset:192
	s_nop 0
	v_pk_fma_f32 v[62:63], v[156:157], v[12:13], v[148:149] neg_lo:[1,0,0] neg_hi:[1,0,0]
	s_nop 0
	v_pk_mul_f32 v[76:77], v[62:63], v[62:63]
	v_pk_fma_f32 v[78:79], v[156:157], v[14:15], v[150:151] neg_lo:[1,0,0] neg_hi:[1,0,0]
	v_add_f32_e32 v61, v76, v77
	v_pk_mul_f32 v[80:81], v[78:79], v[78:79]
	s_nop 0
	v_add_f32_e32 v61, v80, v61
	v_add_f32_e32 v61, v81, v61
	ds_bpermute_b32 v44, v44, v61
	s_waitcnt lgkmcnt(0)
	v_add_f32_e32 v44, v61, v44
	ds_bpermute_b32 v45, v45, v44
	s_waitcnt lgkmcnt(0)
	v_add_f32_e32 v44, v44, v45
	ds_bpermute_b32 v45, v46, v44
	s_waitcnt lgkmcnt(0)
	v_add_f32_e32 v44, v44, v45
	ds_bpermute_b32 v45, v47, v44
	s_waitcnt lgkmcnt(0)
	v_add_f32_e32 v44, v44, v45
	ds_bpermute_b32 v45, v60, v44
	s_waitcnt lgkmcnt(0)
	v_add_f32_e32 v44, v44, v45
	v_fmamk_f32 v44, v44, 0x3c000000, v158
	v_cmp_gt_f32_e32 vcc, s82, v44
	v_mul_f32_e32 v45, 0x4b800000, v44
	s_nop 0
	v_cndmask_b32_e32 v44, v44, v45, vcc
	v_rsq_f32_e32 v44, v44
	s_nop 0
	v_mul_f32_e32 v45, 0x45800000, v44
	v_cndmask_b32_e32 v44, v44, v45, vcc
	v_mul_f32_e32 v45, v62, v44
	v_mul_f32_e32 v45, v172, v45
	v_cvt_pk_bf16_f32 v45, v45, v97
	global_store_short v[30:31], v45, off offset:2048
	v_mul_f32_e32 v45, v63, v44
	v_mul_f32_e32 v45, v173, v45
	v_cvt_pk_bf16_f32 v45, v45, v97
	global_store_short v[30:31], v45, off offset:2112
	v_mul_f32_e32 v45, v78, v44
	v_mul_f32_e32 v44, v79, v44
	v_mul_f32_e32 v45, v174, v45
	v_mul_f32_e32 v44, v175, v44
	v_cvt_pk_bf16_f32 v45, v45, v97
	global_store_short v[30:31], v45, off offset:2176
	v_cvt_pk_bf16_f32 v44, v44, v97
	global_store_short v[30:31], v44, off offset:2240
	s_cbranch_execnz .LBB0_169
	s_branch .LBB0_192

; __device__ __forceinline__ void phase_attn_diff(const Params& p, char* lds) {
;     ...
;             if (j == 0) {
; #pragma unroll
;                 for (int r = 0; r < 16; ++r) { f32x4 t = {o[0][r], o[1][r], o[2][r], o[3][r]}; *(f32x4*)(scr + 4 * r) = t; }
.LBB0_192:
	global_store_dwordx4 v[28:29], v[64:67], off
	global_store_dwordx4 v[28:29], v[68:71], off offset:16
	global_store_dwordx4 v[28:29], v[72:75], off offset:32
	global_store_dwordx4 v[28:29], v[0:3], off offset:48
	global_store_dwordx4 v[28:29], v[16:19], off offset:64
	global_store_dwordx4 v[28:29], v[32:35], off offset:80
	global_store_dwordx4 v[28:29], v[48:51], off offset:96
	global_store_dwordx4 v[28:29], v[4:7], off offset:112
	global_store_dwordx4 v[28:29], v[20:23], off offset:128
	global_store_dwordx4 v[28:29], v[36:39], off offset:144
	global_store_dwordx4 v[28:29], v[52:55], off offset:160
	global_store_dwordx4 v[28:29], v[8:11], off offset:176
	global_store_dwordx4 v[28:29], v[24:27], off offset:192
	global_store_dwordx4 v[28:29], v[40:43], off offset:208
	global_store_dwordx4 v[28:29], v[56:59], off offset:224
	global_store_dwordx4 v[28:29], v[12:15], off offset:240
	s_branch .LBB0_169

; __device__ __forceinline__ unsigned cvt_pk_bf16(float lo, float hi) { unsigned r; asm volatile("v_cvt_pk_bf16_f32 %0, %1, %2" : "=v"(r) : "v"(lo), "v"(hi)); return r; }
; __device__ __forceinline__ int crow(int r, int hi) { return (r & 3) + 8 * (r >> 2) + 4 * hi; }
; template <int DQK, int DK1, int LDQ, int LDK, int LDKR, int LDV, int NQL, int SDEPTH>
; __device__ __forceinline__ void attn_core(const AttnArgs& a, char* lds, f32x16 (&o)[4]) {
;     ...
;     if (hi == 0) li_l[r32] = l_reg; asm volatile("s_waitcnt lgkmcnt(0)" ::: "memory");
; #pragma unroll
;     for (int r = 0; r < 16; ++r) { const float rl = __builtin_amdgcn_rcpf(li_l[crow(r, hi)]);
; #pragma unroll
;         for (int d = 0; d < 4; ++d) o[d][r] *= rl; }
; __device__ __forceinline__ void phase_attn_mla(const Params& p, char* lds) {
;     ...
;         bf16_t* Ow = O + (size_t)(row0 + wid * 32 + 4 * hi) * 1024 + h * 128 + r32;
;         asm volatile("" : "+v"(Ow));
; #pragma unroll
;         for (int r = 0; r < 16; ++r) { bf16_t* Or = Ow + (size_t)((r & 3) + 8 * (r >> 2)) * 1024;
; #pragma unroll
;             for (int d0 = 0; d0 < 4; ++d0) Or[d0 * 32] = (bf16_t)(cvt_pk_bf16(o[d0][r], 0.f) & 0xffffu); }
.LBB0_200:
	s_or_b64 exec, exec, s[14:15]
	s_waitcnt lgkmcnt(0)
	v_add_u32_e32 v72, v161, v96
	ds_read_b128 v[64:67], v72
	ds_read_b128 v[68:71], v72 offset:32
	s_lshl_b32 s12, s24, 8
	s_mov_b32 s13, s36
	v_mov_b32_e32 v161, v97
	s_waitcnt lgkmcnt(1)
	v_rcp_f32_e32 v64, v64
	v_rcp_f32_e32 v65, v65
	s_movk_i32 s3, 0x4000
	s_mov_b32 s2, 0xc000
	v_mul_f32_e32 v48, v48, v64
	v_mul_f32_e32 v32, v32, v64
	v_mul_f32_e32 v73, v16, v64
	v_mul_f32_e32 v64, v0, v64
	v_mul_f32_e32 v49, v49, v65
	v_rcp_f32_e32 v0, v66
	v_mul_f32_e32 v33, v33, v65
	v_mul_f32_e32 v66, v17, v65
	v_mul_f32_e32 v65, v1, v65
	v_rcp_f32_e32 v1, v67
	v_mul_f32_e32 v50, v50, v0
	v_mul_f32_e32 v34, v34, v0
	v_mul_f32_e32 v67, v18, v0
	v_mul_f32_e32 v74, v2, v0
	v_mul_f32_e32 v51, v51, v1
	s_waitcnt lgkmcnt(0)
	v_rcp_f32_e32 v0, v68
	v_mul_f32_e32 v35, v35, v1
	v_mul_f32_e32 v68, v19, v1
	v_mul_f32_e32 v75, v3, v1
	v_rcp_f32_e32 v1, v69
	v_mul_f32_e32 v52, v52, v0
	v_mul_f32_e32 v36, v36, v0
	v_mul_f32_e32 v20, v20, v0
	v_mul_f32_e32 v4, v4, v0
	v_mul_f32_e32 v53, v53, v1
	v_mul_f32_e32 v37, v37, v1
	v_mul_f32_e32 v21, v21, v1
	v_mul_f32_e32 v5, v5, v1
	ds_read_b128 v[0:3], v72 offset:64
	v_rcp_f32_e32 v16, v70
	v_rcp_f32_e32 v69, v71
	v_mul_f32_e32 v54, v54, v16
	v_mul_f32_e32 v38, v38, v16
	v_mul_f32_e32 v22, v22, v16
	v_mul_f32_e32 v6, v6, v16
	ds_read_b128 v[16:19], v72 offset:96
	s_waitcnt lgkmcnt(1)
	v_rcp_f32_e32 v0, v0
	v_rcp_f32_e32 v1, v1
	s_waitcnt lgkmcnt(0)
	s_barrier
	v_mul_f32_e32 v56, v56, v0
	v_mul_f32_e32 v40, v40, v0
	v_mul_f32_e32 v24, v24, v0
	v_mul_f32_e32 v8, v8, v0
	v_rcp_f32_e32 v0, v2
	v_mul_f32_e32 v57, v57, v1
	v_mul_f32_e32 v41, v41, v1
	v_mul_f32_e32 v25, v25, v1
	v_mul_f32_e32 v9, v9, v1
	v_rcp_f32_e32 v1, v3
	v_mul_f32_e32 v58, v58, v0
	v_mul_f32_e32 v42, v42, v0
	v_mul_f32_e32 v26, v26, v0
	v_mul_f32_e32 v10, v10, v0
	v_rcp_f32_e32 v0, v16
	v_mul_f32_e32 v59, v59, v1
	v_mul_f32_e32 v16, v43, v1
	v_mul_f32_e32 v27, v27, v1
	v_mul_f32_e32 v11, v11, v1
	v_rcp_f32_e32 v1, v17
	v_mul_f32_e32 v43, v60, v0
	v_mul_f32_e32 v17, v44, v0
	v_mul_f32_e32 v28, v28, v0
	v_mul_f32_e32 v12, v12, v0
	v_rcp_f32_e32 v0, v18
	v_mul_f32_e32 v44, v61, v1
	v_mul_f32_e32 v18, v45, v1
	v_mul_f32_e32 v29, v29, v1
	v_mul_f32_e32 v13, v13, v1
	v_rcp_f32_e32 v1, v19
	v_mul_f32_e32 v45, v62, v0
	v_mul_f32_e32 v19, v46, v0
	v_mul_f32_e32 v30, v30, v0
	v_mul_f32_e32 v14, v14, v0
	v_add_u32_e32 v0, s23, v180
	v_mul_f32_e32 v46, v63, v1
	v_mul_f32_e32 v47, v47, v1
	v_mul_f32_e32 v31, v31, v1
	v_mul_f32_e32 v15, v15, v1
	v_ashrrev_i32_e32 v1, 31, v0
	v_lshlrev_b64 v[0:1], 11, v[0:1]
	v_lshl_add_u64 v[0:1], s[16:17], 0, v[0:1]
	v_lshl_add_u64 v[0:1], v[0:1], 0, s[12:13]
	v_lshl_add_u64 v[0:1], v[0:1], 0, v[160:161]
	v_cvt_pk_bf16_f32 v2, v48, v97
	global_store_short v[0:1], v2, off
	v_cvt_pk_bf16_f32 v2, v32, v97
	global_store_short v[0:1], v2, off offset:64
	v_cvt_pk_bf16_f32 v2, v73, v97
	global_store_short v[0:1], v2, off offset:128
	v_cvt_pk_bf16_f32 v2, v64, v97
	global_store_short v[0:1], v2, off offset:192
	v_cvt_pk_bf16_f32 v2, v49, v97
	global_store_short v[0:1], v2, off offset:2048
	v_cvt_pk_bf16_f32 v2, v33, v97
	global_store_short v[0:1], v2, off offset:2112
	v_cvt_pk_bf16_f32 v2, v66, v97
	global_store_short v[0:1], v2, off offset:2176
	v_cvt_pk_bf16_f32 v2, v65, v97
	global_store_short v[0:1], v2, off offset:2240
	v_add_co_u32_e32 v2, vcc, s83, v0
	v_cvt_pk_bf16_f32 v32, v50, v97
	v_mul_f32_e32 v55, v55, v69
	s_nop 0
	v_addc_co_u32_e32 v3, vcc, 0, v1, vcc
	global_store_short v[2:3], v32, off
	v_cvt_pk_bf16_f32 v32, v34, v97
	global_store_short v[2:3], v32, off offset:64
	v_cvt_pk_bf16_f32 v32, v67, v97
	global_store_short v[2:3], v32, off offset:128
	v_cvt_pk_bf16_f32 v32, v74, v97
	global_store_short v[2:3], v32, off offset:192
	v_cvt_pk_bf16_f32 v32, v51, v97
	global_store_short v[2:3], v32, off offset:2048
	v_cvt_pk_bf16_f32 v32, v35, v97
	global_store_short v[2:3], v32, off offset:2112
	v_cvt_pk_bf16_f32 v32, v68, v97
	global_store_short v[2:3], v32, off offset:2176
	v_cvt_pk_bf16_f32 v32, v75, v97
	global_store_short v[2:3], v32, off offset:2240
	v_add_co_u32_e32 v2, vcc, s3, v0
	v_cvt_pk_bf16_f32 v32, v52, v97
	v_mul_f32_e32 v39, v39, v69
	s_nop 0
	v_addc_co_u32_e32 v3, vcc, 0, v1, vcc
	global_store_short v[2:3], v32, off
	v_cvt_pk_bf16_f32 v32, v36, v97
	global_store_short v[2:3], v32, off offset:64
; __device__ __forceinline__ unsigned cvt_pk_bf16(float lo, float hi) { unsigned r; asm volatile("v_cvt_pk_bf16_f32 %0, %1, %2" : "=v"(r) : "v"(lo), "v"(hi)); return r; }
; __device__ __forceinline__ void phase_attn_mla(const Params& p, char* lds) {
;     ...
;     for (int it = blockIdx.x; it < 1024 + 128; it += gridDim.x) {
;     ...
;         bf16_t* Ow = O + (size_t)(row0 + wid * 32 + 4 * hi) * 1024 + h * 128 + r32;
;         asm volatile("" : "+v"(Ow));
; #pragma unroll
;         for (int r = 0; r < 16; ++r) { bf16_t* Or = Ow + (size_t)((r & 3) + 8 * (r >> 2)) * 1024;
; #pragma unroll
;             for (int d0 = 0; d0 < 4; ++d0) Or[d0 * 32] = (bf16_t)(cvt_pk_bf16(o[d0][r], 0.f) & 0xffffu); }
	v_cvt_pk_bf16_f32 v20, v20, v97
	global_store_short v[2:3], v20, off offset:128
	v_cvt_pk_bf16_f32 v4, v4, v97
	global_store_short v[2:3], v4, off offset:192
	v_cvt_pk_bf16_f32 v4, v53, v97
	global_store_short v[2:3], v4, off offset:2048
	v_cvt_pk_bf16_f32 v4, v37, v97
	global_store_short v[2:3], v4, off offset:2112
	v_cvt_pk_bf16_f32 v4, v21, v97
	global_store_short v[2:3], v4, off offset:2176
	v_cvt_pk_bf16_f32 v4, v5, v97
	global_store_short v[2:3], v4, off offset:2240
	v_add_co_u32_e32 v2, vcc, s59, v0
	v_cvt_pk_bf16_f32 v4, v54, v97
	v_mul_f32_e32 v23, v23, v69
	s_nop 0
	v_addc_co_u32_e32 v3, vcc, 0, v1, vcc
	global_store_short v[2:3], v4, off
	v_cvt_pk_bf16_f32 v4, v38, v97
	global_store_short v[2:3], v4, off offset:64
	v_cvt_pk_bf16_f32 v4, v22, v97
	global_store_short v[2:3], v4, off offset:128
	v_cvt_pk_bf16_f32 v4, v6, v97
	global_store_short v[2:3], v4, off offset:192
	v_cvt_pk_bf16_f32 v4, v55, v97
	global_store_short v[2:3], v4, off offset:2048
	v_cvt_pk_bf16_f32 v4, v39, v97
	global_store_short v[2:3], v4, off offset:2112
	v_cvt_pk_bf16_f32 v4, v23, v97
	v_mul_f32_e32 v7, v7, v69
	global_store_short v[2:3], v4, off offset:2176
	v_cvt_pk_bf16_f32 v4, v7, v97
	global_store_short v[2:3], v4, off offset:2240
	v_add_co_u32_e32 v2, vcc, s67, v0
	v_cvt_pk_bf16_f32 v4, v56, v97
	s_mov_b32 s3, 0x9000
	s_nop 0
	v_addc_co_u32_e32 v3, vcc, 0, v1, vcc
	global_store_short v[2:3], v4, off
	v_cvt_pk_bf16_f32 v4, v40, v97
	global_store_short v[2:3], v4, off offset:64
	v_cvt_pk_bf16_f32 v4, v24, v97
	global_store_short v[2:3], v4, off offset:128
	v_cvt_pk_bf16_f32 v4, v8, v97
	global_store_short v[2:3], v4, off offset:192
	v_cvt_pk_bf16_f32 v4, v57, v97
	global_store_short v[2:3], v4, off offset:2048
	v_cvt_pk_bf16_f32 v4, v41, v97
	global_store_short v[2:3], v4, off offset:2112
	v_cvt_pk_bf16_f32 v4, v25, v97
	global_store_short v[2:3], v4, off offset:2176
	v_cvt_pk_bf16_f32 v4, v9, v97
	global_store_short v[2:3], v4, off offset:2240
	v_add_co_u32_e32 v2, vcc, s3, v0
	v_cvt_pk_bf16_f32 v4, v58, v97
	s_mov_b32 s3, 0xd000
	s_nop 0
	v_addc_co_u32_e32 v3, vcc, 0, v1, vcc
	global_store_short v[2:3], v4, off
	v_cvt_pk_bf16_f32 v4, v42, v97
	global_store_short v[2:3], v4, off offset:64
	v_cvt_pk_bf16_f32 v4, v26, v97
	global_store_short v[2:3], v4, off offset:128
	v_cvt_pk_bf16_f32 v4, v10, v97
	global_store_short v[2:3], v4, off offset:192
	v_cvt_pk_bf16_f32 v4, v59, v97
	global_store_short v[2:3], v4, off offset:2048
	v_cvt_pk_bf16_f32 v4, v16, v97
	global_store_short v[2:3], v4, off offset:2112
	v_cvt_pk_bf16_f32 v4, v27, v97
	global_store_short v[2:3], v4, off offset:2176
	v_cvt_pk_bf16_f32 v4, v11, v97
	global_store_short v[2:3], v4, off offset:2240
	v_add_co_u32_e32 v2, vcc, s2, v0
	v_cvt_pk_bf16_f32 v4, v43, v97
	s_nop 1
	v_addc_co_u32_e32 v3, vcc, 0, v1, vcc
	global_store_short v[2:3], v4, off
	v_cvt_pk_bf16_f32 v4, v17, v97
	global_store_short v[2:3], v4, off offset:64
	v_cvt_pk_bf16_f32 v4, v28, v97
	global_store_short v[2:3], v4, off offset:128
	v_cvt_pk_bf16_f32 v4, v12, v97
	global_store_short v[2:3], v4, off offset:192
	v_cvt_pk_bf16_f32 v4, v44, v97
	global_store_short v[2:3], v4, off offset:2048
	v_cvt_pk_bf16_f32 v4, v18, v97
	global_store_short v[2:3], v4, off offset:2112
	v_cvt_pk_bf16_f32 v4, v29, v97
	v_add_co_u32_e32 v0, vcc, s3, v0
	global_store_short v[2:3], v4, off offset:2176
	v_cvt_pk_bf16_f32 v4, v13, v97
	global_store_short v[2:3], v4, off offset:2240
	v_cvt_pk_bf16_f32 v2, v45, v97
	v_addc_co_u32_e32 v1, vcc, 0, v1, vcc
	global_store_short v[0:1], v2, off
	v_cvt_pk_bf16_f32 v2, v19, v97
	global_store_short v[0:1], v2, off offset:64
	v_cvt_pk_bf16_f32 v2, v30, v97
	global_store_short v[0:1], v2, off offset:128
	v_cvt_pk_bf16_f32 v2, v14, v97
	global_store_short v[0:1], v2, off offset:192
	v_cvt_pk_bf16_f32 v2, v46, v97
	global_store_short v[0:1], v2, off offset:2048
	v_cvt_pk_bf16_f32 v2, v47, v97
	global_store_short v[0:1], v2, off offset:2112
	v_cvt_pk_bf16_f32 v2, v31, v97
	global_store_short v[0:1], v2, off offset:2176
	v_cvt_pk_bf16_f32 v2, v15, v97
	global_store_short v[0:1], v2, off offset:2240
	s_load_dword s12, s[88:89], 0x10
	s_load_dword s14, s[88:89], 0x0
	s_waitcnt lgkmcnt(0)
	s_lshr_b32 s12, s12, 16
	s_cmp_lg_u32 s12, 0
	s_cselect_b64 s[12:13], -1, 0
	s_cmp_lg_u64 s[12:13], 0
	s_addc_u32 s22, s14, s22
	s_cmpk_gt_i32 s22, 0x47f
	s_cbranch_scc1 .LBB0_236
